# attention phase: one static s_setprio 1 for the trailing virtual block (waves 4-7), reset to 0 at phase exit
# speedup vs baseline: 1.0028x; 1.0028x over previous
; DI int bidx() { int t = __builtin_amdgcn_readfirstlane((int)(blockIdx.x * 2 + (threadIdx.x >> 8))); asm volatile("" : "+s"(t)); return t; }
; DI int gdim() { int t = gridDim.x * 2; asm volatile("" : "+s"(t)); return t; }
; DI void phase_attn(KargPtr p, unsigned char* smem) {
;     for (int idx = bidx(); idx < 6144; idx += gdim()) {
;         if (idx < 4096) {
;             const int j = idx >> 9, g = (idx >> 7) & 3, rem = idx & 127, bh = ((rem & 63) + 13 * j) & 63;
;             const int qb = 31 - 4 * j - ((j & 1) ? 3 - g : g);
;             const int type = ((rem >> 6) + j) & 1;
;             if (type == 0) attn_item<0>(p, bh >> 3, bh & 7, qb, smem);
;             else attn_item<1>(p, bh >> 3, bh & 7, qb, smem);
;         } else {
;             const int j = idx - 4096; const int qb = 31 - (j >> 6), bh = j & 63;
;             attn_item<2>(p, bh >> 3, bh & 7, qb, smem);
;         }
;     }
; }
.LBB0_562:
	s_and_b64 vcc, exec, s[4:5]
	s_cbranch_vccz .LBB0_631
	s_cmp_eq_u32 s3, 0
	s_cbranch_scc1 .Lattn_noprio
	s_setprio 1
.Lattn_noprio:
	v_readfirstlane_b32 s26, v204
	s_branch .LBB0_566

; DI int bidx() { int t = __builtin_amdgcn_readfirstlane((int)(blockIdx.x * 2 + (threadIdx.x >> 8))); asm volatile("" : "+s"(t)); return t; }
; DI int gdim() { int t = gridDim.x * 2; asm volatile("" : "+s"(t)); return t; }
; DI void phase_attn(KargPtr p, unsigned char* smem) {
;     for (int idx = bidx(); idx < 6144; idx += gdim()) {
;         if (idx < 4096) {
;             const int j = idx >> 9, g = (idx >> 7) & 3, rem = idx & 127, bh = ((rem & 63) + 13 * j) & 63;
;             const int qb = 31 - 4 * j - ((j & 1) ? 3 - g : g);
;             const int type = ((rem >> 6) + j) & 1;
;             if (type == 0) attn_item<0>(p, bh >> 3, bh & 7, qb, smem);
;             else attn_item<1>(p, bh >> 3, bh & 7, qb, smem);
;         } else {
;             const int j = idx - 4096; const int qb = 31 - (j >> 6), bh = j & 63;
;             attn_item<2>(p, bh >> 3, bh & 7, qb, smem);
;         }
;     }
; }
.LBB0_631:
	s_setprio 0
	s_mov_b64 s[4:5], 0
